# P7: workgroups with blockIdx bit 3 set run their gated-conv items before the attention units (HBM streaming of one half overlaps prompt attention of the other) on top of k3
# speedup vs baseline: 1.0100x; 1.0100x over previous
; #define GAS __attribute__((address_space(1)))
; #define LAS __attribute__((address_space(3)))
; __device__ __forceinline__ void prompt_unit(Frame& F, const Args& A, int b, int hk) {
;     const bf16* PROJ = (const bf16*)(A.ws + WS_PROJ); bf16* MIX = (bf16*)(A.ws + WS_MIX);
;     LAS unsigned char* lds = F.lds;
;     fill_lut(lds, A.in[I_RB], hk, F.tid);
;     v4u kqa[8], vqa[8];
; #pragma unroll
;     for (int i = 0; i < 8; ++i) { const int cid = F.tid + 512 * i, kidx = cid >> 4, ch = cid & 15; const int row = 128 * (b - 1) + kidx, rowc = row < 0 ? 0 : row;
;         const bf16* p = PROJ + (size_t)rowc * NPROJ + 128 * hk + 8 * ch; kqa[i] = *(const GAS v4u*)(p + C_K); vqa[i] = *(const GAS v4u*)(p + C_V); }
; #pragma unroll
;     for (int i = 0; i < 8; ++i) { const int cid = F.tid + 512 * i, kidx = cid >> 4, ch = cid & 15; const int row = 128 * (b - 1) + kidx;
;         v4u kq = kqa[i], vq = vqa[i];
;         if (row < 0) { kq = (v4u){0u, 0u, 0u, 0u}; vq = (v4u){0u, 0u, 0u, 0u}; }
;         stage_kv(lds, kidx, ch, kq, vq);
;         if (b == SEQ / 128 - 1 && kidx >= 128) {
;             store8_f32(A.out + O_KWP + (size_t)(kidx - 128) * 512 + 128 * hk + 8 * ch, kq);
;             store8_f32(A.out + O_VWP + (size_t)(kidx - 128) * 512 + 128 * hk + 8 * ch, vq); }
;     }
;     __syncthreads();
;     const int g = F.wave >> 1, half = F.wave & 1, c = F.lane & 31, h = F.lane >> 5, head = 4 * hk + g;
;     const float sink = A.in[I_SINK][head];
; #pragma unroll 1
;     for (int qt = 0; qt < 2; ++qt) { const int r = 64 * half + 32 * qt + c, row = 128 * b + r;
;         bf16x8 Q[8];
; #pragma unroll
;         for (int ks = 0; ks < 8; ++ks) Q[ks] = *(const GAS bf16x8*)(PROJ + (size_t)row * NPROJ + 128 * head + 16 * ks + 8 * h);
;         attn_qtile<5>(lds, 2 * half + qt, Q, r, b == 0 ? 128 : 0, 256, g, sink, MIX + (size_t)row * D + 128 * head, F.lane);
; __device__ __forceinline__ void mixer_phase(Frame& F, const Args& A) {
;     ...
;     for (int u = F.vcu; u < 256 * (PROBE_P7 == 1 ? 2 : 1); u += F.G) prompt_unit(F, A, (u & 255) >> 2, u & 3);
.Lp7_again:
	s_cmpk_eq_i32 s33, 0x100
	s_cbranch_scc0 .Lp7_norm
	s_cmp_eq_u32 s101, 7
	s_cbranch_scc1 .Lp7_norm
	s_bitcmp1_b32 s50, 3
	s_cbranch_scc0 .Lp7_norm
	v_writelane_b32 v253, s17, 0
	v_writelane_b32 v253, s18, 1
	v_writelane_b32 v253, s19, 2
	v_writelane_b32 v253, s20, 3
	v_writelane_b32 v253, s21, 4
	v_writelane_b32 v253, s22, 5
	v_writelane_b32 v253, s23, 6
	v_writelane_b32 v253, s48, 7
	v_writelane_b32 v253, s54, 8
	v_writelane_b32 v253, s58, 9
	v_writelane_b32 v253, s59, 10
	v_writelane_b32 v253, s60, 11
	v_writelane_b32 v253, s61, 12
	v_writelane_b32 v253, s62, 13
	v_writelane_b32 v253, s63, 14
	v_writelane_b32 v253, s66, 15
	v_writelane_b32 v253, s67, 16
	v_writelane_b32 v253, s88, 17
	v_writelane_b32 v253, s94, 18
	v_writelane_b32 v253, s95, 19
	v_writelane_b32 v253, s96, 20
	v_writelane_b32 v253, s97, 21
	v_mov_b32_e32 v223, v14
	v_mov_b32_e32 v224, v15
	v_mov_b32_e32 v225, v16
	v_mov_b32_e32 v226, v17
	v_mov_b32_e32 v227, v18
	v_mov_b32_e32 v228, v19
	v_mov_b32_e32 v229, v20
	v_mov_b32_e32 v230, v21
	v_mov_b32_e32 v231, v25
	s_mov_b32 s101, 6
	s_mov_b64 s[36:37], s[96:97]
	s_mov_b64 s[38:39], s[58:59]
	s_mov_b64 s[44:45], s[94:95]
	s_branch .LBB0_641
.Lp7_norm:
	s_add_i32 s0, 0, 0x11000
	v_readlane_b32 s1, v252, 2
	s_cmpk_gt_i32 s1, 0xff
	s_movk_i32 s1, 0x204
	v_cmp_gt_u32_e64 s[2:3], s1, v0
	v_lshrrev_b32_e32 v163, 4, v0
	v_and_b32_e32 v4, 15, v0
	v_lshrrev_b32_e32 v3, 3, v0
	s_movk_i32 s1, 0x53
	v_mul_u32_u24_e32 v2, 0x1080, v4
	v_and_b32_e32 v154, 8, v3
	v_and_b32_e32 v3, 8, v163
	v_bitop3_b32 v151, v163, s1, 64 bitop3:0xc8
	s_movk_i32 s1, 0x93
	v_mov_b32_e32 v156, 0x80
	v_add3_u32 v155, s0, v2, v3
	v_bitop3_b32 v2, v163, s1, v156 bitop3:0xc8
	v_lshlrev_b32_e32 v3, 1, v2
	v_lshlrev_b32_e32 v2, 1, v154
	v_add3_u32 v170, v155, v3, v2
	v_and_b32_e32 v150, 31, v0
	v_lshrrev_b32_e32 v3, 2, v0
	v_lshrrev_b32_e32 v6, 5, v162
	v_and_b32_e32 v5, 8, v3
	v_lshlrev_b32_e32 v7, 4, v6
	v_lshlrev_b32_e32 v149, 2, v6
	v_mul_u32_u24_e32 v6, 0x210, v150
	v_lshlrev_b32_e32 v171, 3, v4
	s_mov_b32 s9, 0
	s_movk_i32 s14, 0x110
	v_mul_u32_u24_e32 v165, 0x110, v163
	v_lshlrev_b32_e32 v153, 4, v4
	v_and_b32_e32 v152, 19, v163
	v_mov_b32_e32 v111, 0
	v_add_u32_e32 v148, 0, v7
	v_add3_u32 v172, s0, v7, v6
	v_lshlrev_b32_e32 v122, 1, v5
	v_lshlrev_b32_e32 v124, 1, v149
	v_lshlrev_b32_e32 v126, 2, v171
	s_cbranch_scc1 .LBB0_627
	v_or_b32_e32 v4, 0x200, v0
	v_lshrrev_b32_e32 v159, 4, v4
	v_lshrrev_b32_e32 v4, 3, v4
	v_and_b32_e32 v4, 0x66, v4
	v_and_b32_e32 v3, 16, v3
	v_or_b32_e32 v5, 0x600, v0
	v_add3_u32 v173, v155, v4, v3
	v_lshlrev_b32_e32 v4, 1, v151
	v_add3_u32 v174, v155, v4, v2
	v_lshrrev_b32_e32 v4, 3, v5
	v_or_b32_e32 v6, 0xa00, v0
	v_and_b32_e32 v4, 0xe6, v4
	v_add3_u32 v175, v155, v4, v3
	v_lshrrev_b32_e32 v4, 3, v6
	s_movk_i32 s0, 0x1ff
	v_and_b32_e32 v4, 0x166, v4
	v_cmp_lt_u32_e64 s[4:5], s0, v0
	v_add3_u32 v176, v155, v4, v3
	s_movk_i32 s0, 0xd3
	v_mov_b32_e32 v4, 0xc0
	s_lshr_b32 s15, s71, 7
	v_bitop3_b32 v4, v163, s0, v4 bitop3:0xc8
	s_mul_i32 s0, s15, 0x210
	s_bfe_u32 s8, s71, 0x10006
	s_add_i32 s17, s0, 0
	s_lshl_b32 s16, s8, 1
	s_add_i32 s17, s17, 0x21800
	v_or_b32_e32 v7, 0xe00, v0
	v_lshlrev_b32_e32 v8, 1, v152
	v_lshlrev_b32_e32 v4, 1, v4
	s_add_u32 s0, s28, 0x9000000
	v_and_b32_e32 v110, 0xf0, v164
	v_lshrrev_b32_e32 v160, 4, v5
	v_add3_u32 v169, v155, v8, v2
	v_add3_u32 v177, v155, v4, v2
	v_lshrrev_b32_e32 v2, 3, v7
	s_addc_u32 s1, s29, 0
	v_lshl_add_u64 v[112:113], s[52:53], 0, v[110:111]
	v_and_b32_e32 v2, 0x1e6, v2
	v_or_b32_e32 v110, 0xffffff80, v160
	s_add_u32 s6, s28, 0x9040000
	v_add3_u32 v178, v155, v2, v3
	v_lshlrev_b64 v[2:3], 11, v[110:111]
	s_addc_u32 s7, s29, 0
	v_lshl_add_u64 v[4:5], s[0:1], 0, v[2:3]
	v_mov_b32_e32 v127, v111
	v_lshl_add_u64 v[2:3], s[6:7], 0, v[2:3]
	v_lshlrev_b32_e32 v110, 11, v163
	v_lshl_add_u64 v[120:121], v[2:3], 0, v[126:127]
	v_lshl_add_u64 v[2:3], s[0:1], 0, v[110:111]
	v_lshrrev_b32_e32 v161, 4, v6
	v_lshl_add_u64 v[128:129], v[2:3], 0, v[126:127]
	v_lshl_add_u64 v[2:3], s[6:7], 0, v[110:111]
	v_lshl_add_u64 v[130:131], v[2:3], 0, v[126:127]
	v_lshlrev_b32_e32 v2, 11, v161
	v_mov_b32_e32 v3, v111
	v_lshl_add_u64 v[118:119], v[4:5], 0, v[126:127]
	v_add_u32_e32 v4, 0xfffc0000, v2
	v_lshl_add_u64 v[2:3], s[0:1], 0, v[2:3]
	v_or_b32_e32 v110, 0x20000, v110
	v_lshl_add_u64 v[134:135], v[2:3], 0, v[126:127]
	v_lshl_add_u64 v[2:3], s[0:1], 0, v[110:111]
	v_lshl_add_u64 v[136:137], v[2:3], 0, v[126:127]
	v_lshl_add_u64 v[2:3], s[6:7], 0, v[110:111]
	v_lshrrev_b32_e32 v167, 4, v7
	v_lshl_add_u64 v[138:139], v[2:3], 0, v[126:127]
	v_mov_b32_e32 v2, 0xfffc0000
	v_lshl_add_u32 v110, v167, 11, v2
	v_lshl_add_u64 v[2:3], s[0:1], 0, v[110:111]
	v_lshl_add_u64 v[140:141], v[2:3], 0, v[126:127]
	v_lshl_add_u64 v[2:3], s[6:7], 0, v[110:111]
	v_mov_b32_e32 v5, v111
	v_lshl_add_u64 v[142:143], v[2:3], 0, v[126:127]
	v_mbcnt_lo_u32_b32 v2, -1, 0
	v_lshl_add_u64 v[4:5], s[0:1], 0, v[4:5]
	v_mbcnt_hi_u32_b32 v2, -1, v2
	v_lshl_add_u64 v[132:133], v[4:5], 0, v[126:127]
	v_and_b32_e32 v4, 64, v2
	v_xor_b32_e32 v3, 32, v2
	v_add_u32_e32 v4, 64, v4
	v_add_u32_e32 v168, 0, v165
	v_cmp_lt_i32_e32 vcc, v3, v4
	v_mad_u32_u24 v8, v159, s14, 0
	v_mad_u32_u24 v9, v160, s14, 0
	v_add_u32_e32 v10, 0x8800, v168
	v_mad_u32_u24 v11, v161, s14, 0
	v_mad_u32_u24 v6, v167, s14, 0
	v_mov_b32_e32 v123, v111
	v_mov_b32_e32 v125, v111
	v_cndmask_b32_e32 v2, v2, v3, vcc
	v_or_b32_e32 v157, 64, v163
	v_or_b32_e32 v158, 0x80, v163
	v_or_b32_e32 v166, 0xc0, v163
	v_lshl_add_u64 v[114:115], s[52:53], 0, v[122:123]
	v_lshl_add_u64 v[116:117], s[42:43], 0, v[124:125]
	v_lshlrev_b32_e32 v123, 2, v2
	v_lshl_or_b32 v125, s8, 6, v150
	s_movk_i32 s18, 0x3f81
	s_movk_i32 s19, 0x81
	s_movk_i32 s20, 0x42
	s_movk_i32 s21, 0x4c
	s_movk_i32 s22, 0x56
	s_movk_i32 s23, 0x62
	s_movk_i32 s48, 0x70
	s_movk_i32 s49, 0x4800
	v_add_u32_e32 v127, v8, v153
	v_add_u32_e32 v179, v9, v153
	v_add_u32_e32 v180, v11, v153
	v_add_u32_e32 v181, v6, v153
	s_movk_i32 s54, 0x7fff
	v_add_u32_e32 v182, v10, v153
	v_mov_b32_e32 v183, 0xf149f2ca
	v_mov_b32_e32 v184, 1
	v_readlane_b32 s55, v252, 2

; __device__ __forceinline__ void mixer_phase(Frame& F, const Args& A) {
;     ...
;     for (int u = F.vcu; u < 256 * (PROBE_P7 == 1 ? 2 : 1); u += F.G) prompt_unit(F, A, (u & 255) >> 2, u & 3);
;     for (int u = F.vcu; u < 512 * (PROBE_P7 == 2 ? 2 : 1); u += F.G) sample_unit(F, A, (u & 511) >> 2, u & 3);
;     for (int u = F.vcu * NWAVES + F.wave; u < (M / 8) * 8 * (PROBE_P7 == 3 ? 2 : 1); u += F.G * NWAVES) conv_item(F, A, u % ((M / 8) * 8));
.LBB0_641:
	s_cmp_eq_u32 s101, 7
	s_cbranch_scc0 .Lp7_doconv
	s_mov_b64 s[96:97], s[36:37]
	s_mov_b64 s[58:59], s[38:39]
	s_mov_b64 s[94:95], s[44:45]
	s_mov_b32 s101, 0
	s_branch .LBB0_659

; __device__ __forceinline__ void mixer_phase(Frame& F, const Args& A) {
;     ...
;     for (int u = F.vcu; u < 256 * (PROBE_P7 == 1 ? 2 : 1); u += F.G) prompt_unit(F, A, (u & 255) >> 2, u & 3);
;     for (int u = F.vcu; u < 512 * (PROBE_P7 == 2 ? 2 : 1); u += F.G) sample_unit(F, A, (u & 511) >> 2, u & 3);
;     for (int u = F.vcu * NWAVES + F.wave; u < (M / 8) * 8 * (PROBE_P7 == 3 ? 2 : 1); u += F.G * NWAVES) conv_item(F, A, u % ((M / 8) * 8));
.LBB0_658:
	s_mov_b64 s[94:95], s[44:45]
	s_cmp_eq_u32 s101, 6
	s_cbranch_scc0 .LBB0_659
	s_mov_b32 s101, 7
	v_readlane_b32 s17, v253, 0
	v_readlane_b32 s18, v253, 1
	v_readlane_b32 s19, v253, 2
	v_readlane_b32 s20, v253, 3
	v_readlane_b32 s21, v253, 4
	v_readlane_b32 s22, v253, 5
	v_readlane_b32 s23, v253, 6
	v_readlane_b32 s48, v253, 7
	v_readlane_b32 s54, v253, 8
	v_readlane_b32 s58, v253, 9
	v_readlane_b32 s59, v253, 10
	v_readlane_b32 s60, v253, 11
	v_readlane_b32 s61, v253, 12
	v_readlane_b32 s62, v253, 13
	v_readlane_b32 s63, v253, 14
	v_readlane_b32 s66, v253, 15
	v_readlane_b32 s67, v253, 16
	v_readlane_b32 s88, v253, 17
	v_readlane_b32 s94, v253, 18
	v_readlane_b32 s95, v253, 19
	v_readlane_b32 s96, v253, 20
	v_readlane_b32 s97, v253, 21
	v_mov_b32_e32 v14, v223
	v_mov_b32_e32 v15, v224
	v_mov_b32_e32 v16, v225
	v_mov_b32_e32 v17, v226
	v_mov_b32_e32 v18, v227
	v_mov_b32_e32 v19, v228
	v_mov_b32_e32 v20, v229
	v_mov_b32_e32 v21, v230
	v_mov_b32_e32 v25, v231
	s_nop 7
	s_branch .Lp7_again
